# P4 epilogue: conv neighbour rows kept packed fp16, masked with v_and and folded with v_fma_mix_f32 (no cvt / mask multiplies)
# speedup vs baseline: 1.0010x; 1.0010x over previous
.Lp4_skew1:
	s_nop 7
	s_nop 1
	s_mov_b32 s94, s18
	s_mov_b32 s34, s28
	v_bfe_u32 v201, v222, 6, 2
	v_bfe_u32 v202, v222, 4, 2
	v_lshlrev_b32_e32 v203, 2, v202
	v_lshl_or_b32 v203, v201, 5, v203
	s_lshl_b32 s4, s94, 7
	v_or_b32_e32 v204, s4, v203
	v_lshlrev_b32_e32 v205, 2, v204
	global_load_dwordx4 v[130:133], v205, s[10:11]
	global_load_dwordx4 v[134:137], v205, s[12:13]
	global_load_dwordx4 v[138:141], v205, s[14:15]
	global_load_dwordx4 v[142:145], v205, s[10:11] offset:64
	global_load_dwordx4 v[146:149], v205, s[12:13] offset:64
	global_load_dwordx4 v[150:153], v205, s[14:15] offset:64
	s_add_i32 s2, s49, s95
	s_cmp_lt_i32 s2, s58
	s_cselect_b32 s35, 1, 0
	s_cselect_b32 s49, s2, s49
	s_mul_hi_i32 s2, s49, 0x2e8ba2e9
	s_lshr_b32 s3, s2, 31
	s_ashr_i32 s2, s2, 6
	s_add_i32 s2, s2, s3
	s_lshl_b32 s3, s2, 4
	s_sub_i32 s4, s7, s3
	s_min_i32 s4, s4, 16
	s_abs_i32 s5, s4
	v_cvt_f32_u32_e32 v199, s5
	s_sub_i32 s20, 0, s5
	s_mulk_i32 s2, 0xfea0
	s_add_i32 s2, s2, s49
	v_rcp_iflag_f32_e32 v199, v199
	s_abs_i32 s19, s2
	s_xor_b32 s18, s2, s4
	s_ashr_i32 s18, s18, 31
	v_mul_f32_e32 v199, 0x4f7ffffe, v199
	v_cvt_u32_f32_e32 v199, v199
	s_nop 1
	v_readfirstlane_b32 s21, v199
	s_mul_i32 s20, s20, s21
	s_mul_hi_u32 s20, s21, s20
	s_add_i32 s21, s21, s20
	s_mul_hi_u32 s20, s19, s21
	s_mul_i32 s21, s20, s5
	s_sub_i32 s19, s19, s21
	s_add_i32 s21, s20, 1
	s_sub_i32 s22, s19, s5
	s_cmp_ge_u32 s19, s5
	s_cselect_b32 s20, s21, s20
	s_cselect_b32 s19, s22, s19
	s_add_i32 s21, s20, 1
	s_cmp_ge_u32 s19, s5
	s_cselect_b32 s5, s21, s20
	s_xor_b32 s5, s5, s18
	s_sub_i32 s18, s5, s18
	s_mul_i32 s4, s18, s4
	s_sub_i32 s2, s2, s4
	s_add_i32 s2, s2, s3
	s_mul_i32 s28, s2, 0xfe
	s_add_i32 s28, s28, -1
	v_lshrrev_b32_e32 v202, 3, v222
	v_lshrrev_b32_e32 v203, 4, v222
	v_xor_b32_e32 v203, v203, v222
	v_and_b32_e32 v203, 7, v203
	v_lshlrev_b32_e32 v210, 4, v203
	v_mov_b32_e32 v200, s46
	v_mov_b32_e32 v201, s47
	v_add_u32_e32 v204, s28, v202
	v_mov_b32_e32 v205, 0
	v_cmp_gt_u32_e32 vcc, s6, v204
	v_lshlrev_b64 v[196:197], 11, v[204:205]
	v_lshl_add_u64 v[196:197], s[64:65], 0, v[196:197]
	v_cndmask_b32_e32 v196, v200, v196, vcc
	v_cndmask_b32_e32 v197, v201, v197, vcc
	v_lshl_add_u64 v[218:219], v[196:197], 0, v[210:211]
	v_add_u32_e32 v204, 64, v204
	v_cmp_gt_u32_e32 vcc, s6, v204
	v_lshlrev_b64 v[196:197], 11, v[204:205]
	v_lshl_add_u64 v[196:197], s[64:65], 0, v[196:197]
	v_cndmask_b32_e32 v196, v200, v196, vcc
	v_cndmask_b32_e32 v197, v201, v197, vcc
	v_lshl_add_u64 v[220:221], v[196:197], 0, v[210:211]
	v_add_u32_e32 v204, 64, v204
	v_cmp_gt_u32_e32 vcc, s6, v204
	v_lshlrev_b64 v[196:197], 11, v[204:205]
	v_lshl_add_u64 v[196:197], s[64:65], 0, v[196:197]
	v_cndmask_b32_e32 v196, v200, v196, vcc
	v_cndmask_b32_e32 v197, v201, v197, vcc
	v_lshl_add_u64 v[224:225], v[196:197], 0, v[210:211]
	v_add_u32_e32 v204, 64, v204
	v_cmp_gt_u32_e32 vcc, s6, v204
	v_lshlrev_b64 v[196:197], 11, v[204:205]
	v_lshl_add_u64 v[196:197], s[64:65], 0, v[196:197]
	v_cndmask_b32_e32 v196, v200, v196, vcc
	v_cndmask_b32_e32 v197, v201, v197, vcc
	v_lshl_add_u64 v[226:227], v[196:197], 0, v[210:211]
	s_lshl_b32 s2, s18, 19
	s_add_u32 s2, s55, s2
	s_addc_u32 s3, s48, 0
	v_lshlrev_b32_e32 v196, 11, v202
	v_add_u32_e32 v196, v196, v210
	v_mov_b32_e32 v197, 0
	v_lshl_add_u64 v[228:229], v[196:197], 0, s[2:3]
	v_readfirstlane_b32 s19, v222
	s_nop 3
	s_lshr_b32 s29, s19, 8
	s_lshr_b32 s19, s19, 6
	s_lshl_b32 s19, s19, 10
	s_mov_b32 s20, 0
	s_mov_b32 s21, 0
	s_mov_b32 s23, 0
	s_mov_b32 m0, s19
	v_lshl_add_u64 v[196:197], v[218:219], 0, s[20:21]
	global_load_lds_dwordx4 v[196:197], off
	s_add_i32 m0, s19, 0x2000
	v_lshl_add_u64 v[198:199], v[220:221], 0, s[20:21]
	global_load_lds_dwordx4 v[198:199], off
	s_add_i32 m0, s19, 0x4000
	v_lshl_add_u64 v[196:197], v[224:225], 0, s[20:21]
	global_load_lds_dwordx4 v[196:197], off
	s_add_i32 m0, s19, 0x6000
	v_lshl_add_u64 v[198:199], v[226:227], 0, s[20:21]
	global_load_lds_dwordx4 v[198:199], off
	s_add_i32 m0, s19, 0x8000
	v_lshl_add_u64 v[196:197], v[228:229], 0, s[20:21]
	global_load_lds_dwordx4 v[196:197], off
	s_add_u32 s22, s20, 0x20000
	s_add_i32 m0, s19, 0xa000
	v_lshl_add_u64 v[198:199], v[228:229], 0, s[22:23]
	global_load_lds_dwordx4 v[198:199], off
	s_add_u32 s22, s20, 0x40000
	s_add_i32 m0, s19, 0xc000
	v_lshl_add_u64 v[196:197], v[228:229], 0, s[22:23]
	global_load_lds_dwordx4 v[196:197], off
	s_add_u32 s22, s20, 0x60000
	s_add_i32 m0, s19, 0xe000
	v_lshl_add_u64 v[198:199], v[228:229], 0, s[22:23]
	global_load_lds_dwordx4 v[198:199], off
	v_and_b32_e32 v200, 15, v222
	v_lshrrev_b32_e32 v201, 8, v222
	v_lshl_or_b32 v200, v201, 7, v200
	v_bfe_u32 v201, v222, 6, 2
	v_bfe_u32 v202, v222, 4, 2
	v_lshlrev_b32_e32 v203, 2, v202
	v_lshl_or_b32 v203, v201, 5, v203
	s_lshl_b32 s4, s94, 7
	v_or_b32_e32 v204, s4, v203
	v_lshlrev_b32_e32 v205, 2, v204
	v_lshlrev_b32_e32 v207, 1, v204
	v_mul_u32_u24_e32 v206, 0x110, v200
	v_lshl_add_u32 v206, v203, 1, v206
	v_add_u32_e32 v206, 0x10000, v206
	v_cvt_pk_f16_f32 v170, v126, v127
	v_cvt_pk_f16_f32 v171, v128, v129
	v_cvt_pk_f16_f32 v172, v118, v119
	v_cvt_pk_f16_f32 v173, v120, v121
	ds_write2_b64 v206, v[170:171], v[172:173] offset1:4
	v_cvt_pk_f16_f32 v174, v110, v111
	v_cvt_pk_f16_f32 v175, v112, v113
	v_cvt_pk_f16_f32 v176, v102, v103
	v_cvt_pk_f16_f32 v177, v104, v105
	v_add_u32_e32 v178, 0x1100, v206
	ds_write2_b64 v178, v[174:175], v[176:177] offset1:4
	v_cvt_pk_f16_f32 v170, v94, v95
	v_cvt_pk_f16_f32 v171, v96, v97
	v_cvt_pk_f16_f32 v172, v86, v87
	v_cvt_pk_f16_f32 v173, v88, v89
	v_add_u32_e32 v178, 0x2200, v206
	ds_write2_b64 v178, v[170:171], v[172:173] offset1:4
	v_cvt_pk_f16_f32 v174, v78, v79
	v_cvt_pk_f16_f32 v175, v80, v81
	v_cvt_pk_f16_f32 v176, v70, v71
	v_cvt_pk_f16_f32 v177, v72, v73
	v_add_u32_e32 v178, 0x3300, v206
	ds_write2_b64 v178, v[174:175], v[176:177] offset1:4
	v_cvt_pk_f16_f32 v170, v62, v63
	v_cvt_pk_f16_f32 v171, v64, v65
	v_cvt_pk_f16_f32 v172, v54, v55
	v_cvt_pk_f16_f32 v173, v56, v57
	v_add_u32_e32 v178, 0x4400, v206
	ds_write2_b64 v178, v[170:171], v[172:173] offset1:4
	v_cvt_pk_f16_f32 v174, v46, v47
	v_cvt_pk_f16_f32 v175, v48, v49
	v_cvt_pk_f16_f32 v176, v38, v39
	v_cvt_pk_f16_f32 v177, v40, v41
	v_add_u32_e32 v178, 0x5500, v206
	ds_write2_b64 v178, v[174:175], v[176:177] offset1:4
	v_cvt_pk_f16_f32 v170, v30, v31
	v_cvt_pk_f16_f32 v171, v32, v33
	v_cvt_pk_f16_f32 v172, v22, v23
	v_cvt_pk_f16_f32 v173, v24, v25
	v_add_u32_e32 v178, 0x6600, v206
	ds_write2_b64 v178, v[170:171], v[172:173] offset1:4
	v_cvt_pk_f16_f32 v174, v14, v15
	v_cvt_pk_f16_f32 v175, v16, v17
	v_cvt_pk_f16_f32 v176, v6, v7
	v_cvt_pk_f16_f32 v177, v8, v9
	v_add_u32_e32 v178, 0x7700, v206
	ds_write2_b64 v178, v[174:175], v[176:177] offset1:4
	v_add_u32_e32 v201, 0xfffffef0, v206
	s_waitcnt lgkmcnt(0)
	s_barrier
	ds_read2_b64 v[154:157], v201 offset1:4
	ds_read2_b64 v[158:161], v201 offset0:68 offset1:72
	s_waitcnt vmcnt(8)
	v_add_u32_e32 v179, 0x1100, v201
	ds_read2_b64 v[162:165], v179 offset1:4
	ds_read2_b64 v[166:169], v179 offset0:68 offset1:72
	v_add_u32_e32 v180, 0, v200
	v_add_u32_e32 v181, s34, v180
	v_add_u32_e32 v182, -1, v180
	v_cmp_gt_u32_e32 vcc, 0xfe, v182
	v_cmp_gt_i32_e64 s[2:3], s6, v181
	v_cmp_gt_i32_e64 s[4:5], s68, v181
	v_mad_u32_u24 v183, v181, s52, v207
	s_and_b64 s[2:3], vcc, s[2:3]
	v_cndmask_b32_e64 v184, v216, v217, s[4:5]
	v_and_b32_e32 v185, v184, v181
	v_cmp_eq_u32_e32 vcc, 0, v185
	s_nop 1
	v_cndmask_b32_e64 v186, -1, 0, vcc
	v_cmp_eq_u32_e32 vcc, v185, v184
	s_nop 1
	v_cndmask_b32_e64 v188, -1, 0, vcc
	s_and_saveexec_b64 s[4:5], s[2:3]
	s_waitcnt lgkmcnt(2)
	v_pk_mul_f32 v[126:127], v[126:127], v[134:135]
	v_pk_mul_f32 v[128:129], v[128:129], v[136:137]
	v_and_b32_e32 v154, v186, v154
	v_and_b32_e32 v155, v186, v155
	v_and_b32_e32 v158, v188, v158
	v_and_b32_e32 v159, v188, v159
	v_fma_mix_f32 v126, v130, v154, v126 op_sel:[0,0,0] op_sel_hi:[0,1,0]
	v_fma_mix_f32 v127, v131, v154, v127 op_sel:[0,1,0] op_sel_hi:[0,1,0]
	v_fma_mix_f32 v128, v132, v155, v128 op_sel:[0,0,0] op_sel_hi:[0,1,0]
	v_fma_mix_f32 v129, v133, v155, v129 op_sel:[0,1,0] op_sel_hi:[0,1,0]
	v_fma_mix_f32 v126, v138, v158, v126 op_sel:[0,0,0] op_sel_hi:[0,1,0]
	v_fma_mix_f32 v127, v139, v158, v127 op_sel:[0,1,0] op_sel_hi:[0,1,0]
	v_fma_mix_f32 v128, v140, v159, v128 op_sel:[0,0,0] op_sel_hi:[0,1,0]
	v_fma_mix_f32 v129, v141, v159, v129 op_sel:[0,1,0] op_sel_hi:[0,1,0]
	v_mul_f32_e32 v190, 0xbfb8aa3b, v126
	v_mul_f32_e32 v191, 0xbfb8aa3b, v127
	v_mul_f32_e32 v192, 0xbfb8aa3b, v128
	v_mul_f32_e32 v193, 0xbfb8aa3b, v129
	v_exp_f32_e32 v190, v190
	v_exp_f32_e32 v191, v191
	v_exp_f32_e32 v192, v192
	v_exp_f32_e32 v193, v193
	v_add_f32_e32 v190, 1.0, v190
	v_add_f32_e32 v191, 1.0, v191
	v_add_f32_e32 v192, 1.0, v192
	v_add_f32_e32 v193, 1.0, v193
	v_rcp_f32_e32 v190, v190
	v_rcp_f32_e32 v191, v191
	v_rcp_f32_e32 v192, v192
	v_rcp_f32_e32 v193, v193
	s_nop 0
	v_pk_mul_f32 v[126:127], v[126:127], v[190:191]
	v_pk_mul_f32 v[128:129], v[128:129], v[192:193]
	v_pk_mul_f32 v[126:127], v[122:123], v[126:127]
	v_pk_mul_f32 v[128:129], v[124:125], v[128:129]
	v_cvt_pk_f16_f32 v126, v126, v127
	v_cvt_pk_f16_f32 v127, v128, v129
	global_store_dwordx2 v183, v[126:127], s[96:97]
	v_pk_mul_f32 v[118:119], v[118:119], v[146:147]
	v_pk_mul_f32 v[120:121], v[120:121], v[148:149]
	v_and_b32_e32 v156, v186, v156
	v_and_b32_e32 v157, v186, v157
	v_and_b32_e32 v160, v188, v160
	v_and_b32_e32 v161, v188, v161
	v_fma_mix_f32 v118, v142, v156, v118 op_sel:[0,0,0] op_sel_hi:[0,1,0]
	v_fma_mix_f32 v119, v143, v156, v119 op_sel:[0,1,0] op_sel_hi:[0,1,0]
	v_fma_mix_f32 v120, v144, v157, v120 op_sel:[0,0,0] op_sel_hi:[0,1,0]
	v_fma_mix_f32 v121, v145, v157, v121 op_sel:[0,1,0] op_sel_hi:[0,1,0]
	v_fma_mix_f32 v118, v150, v160, v118 op_sel:[0,0,0] op_sel_hi:[0,1,0]
	v_fma_mix_f32 v119, v151, v160, v119 op_sel:[0,1,0] op_sel_hi:[0,1,0]
	v_fma_mix_f32 v120, v152, v161, v120 op_sel:[0,0,0] op_sel_hi:[0,1,0]
	v_fma_mix_f32 v121, v153, v161, v121 op_sel:[0,1,0] op_sel_hi:[0,1,0]
	v_mul_f32_e32 v190, 0xbfb8aa3b, v118
	v_mul_f32_e32 v191, 0xbfb8aa3b, v119
	v_mul_f32_e32 v192, 0xbfb8aa3b, v120
	v_mul_f32_e32 v193, 0xbfb8aa3b, v121
	v_exp_f32_e32 v190, v190
	v_exp_f32_e32 v191, v191
	v_exp_f32_e32 v192, v192
	v_exp_f32_e32 v193, v193
	v_add_f32_e32 v190, 1.0, v190
	v_add_f32_e32 v191, 1.0, v191
	v_add_f32_e32 v192, 1.0, v192
	v_add_f32_e32 v193, 1.0, v193
	v_rcp_f32_e32 v190, v190
	v_rcp_f32_e32 v191, v191
	v_rcp_f32_e32 v192, v192
	v_rcp_f32_e32 v193, v193
	s_nop 0
	v_pk_mul_f32 v[118:119], v[118:119], v[190:191]
	v_pk_mul_f32 v[120:121], v[120:121], v[192:193]
	v_pk_mul_f32 v[118:119], v[114:115], v[118:119]
	v_pk_mul_f32 v[120:121], v[116:117], v[120:121]
	v_cvt_pk_f16_f32 v118, v118, v119
	v_cvt_pk_f16_f32 v119, v120, v121
	global_store_dwordx2 v183, v[118:119], s[96:97] offset:32
	s_mov_b64 exec, s[4:5]
	v_add_u32_e32 v179, 0x2200, v201
	ds_read2_b64 v[154:157], v179 offset1:4
	ds_read2_b64 v[158:161], v179 offset0:68 offset1:72
	v_add_u32_e32 v180, 16, v200
	v_add_u32_e32 v181, s34, v180
	v_add_u32_e32 v182, -1, v180
	v_cmp_gt_u32_e32 vcc, 0xfe, v182
	v_cmp_gt_i32_e64 s[2:3], s6, v181
	v_cmp_gt_i32_e64 s[4:5], s68, v181
	v_mad_u32_u24 v183, v181, s52, v207
	s_and_b64 s[2:3], vcc, s[2:3]
	v_cndmask_b32_e64 v184, v216, v217, s[4:5]
	v_and_b32_e32 v185, v184, v181
	v_cmp_eq_u32_e32 vcc, 0, v185
	s_nop 1
	v_cndmask_b32_e64 v186, -1, 0, vcc
	v_cmp_eq_u32_e32 vcc, v185, v184
	s_nop 1
	v_cndmask_b32_e64 v188, -1, 0, vcc
	s_and_saveexec_b64 s[4:5], s[2:3]
	s_waitcnt lgkmcnt(2)
	v_pk_mul_f32 v[110:111], v[110:111], v[134:135]
	v_pk_mul_f32 v[112:113], v[112:113], v[136:137]
	v_and_b32_e32 v162, v186, v162
	v_and_b32_e32 v163, v186, v163
	v_and_b32_e32 v166, v188, v166
	v_and_b32_e32 v167, v188, v167
	v_fma_mix_f32 v110, v130, v162, v110 op_sel:[0,0,0] op_sel_hi:[0,1,0]
	v_fma_mix_f32 v111, v131, v162, v111 op_sel:[0,1,0] op_sel_hi:[0,1,0]
	v_fma_mix_f32 v112, v132, v163, v112 op_sel:[0,0,0] op_sel_hi:[0,1,0]
	v_fma_mix_f32 v113, v133, v163, v113 op_sel:[0,1,0] op_sel_hi:[0,1,0]
	v_fma_mix_f32 v110, v138, v166, v110 op_sel:[0,0,0] op_sel_hi:[0,1,0]
	v_fma_mix_f32 v111, v139, v166, v111 op_sel:[0,1,0] op_sel_hi:[0,1,0]
	v_fma_mix_f32 v112, v140, v167, v112 op_sel:[0,0,0] op_sel_hi:[0,1,0]
	v_fma_mix_f32 v113, v141, v167, v113 op_sel:[0,1,0] op_sel_hi:[0,1,0]
	v_mul_f32_e32 v190, 0xbfb8aa3b, v110
	v_mul_f32_e32 v191, 0xbfb8aa3b, v111
	v_mul_f32_e32 v192, 0xbfb8aa3b, v112
	v_mul_f32_e32 v193, 0xbfb8aa3b, v113
	v_exp_f32_e32 v190, v190
	v_exp_f32_e32 v191, v191
	v_exp_f32_e32 v192, v192
	v_exp_f32_e32 v193, v193
	v_add_f32_e32 v190, 1.0, v190
	v_add_f32_e32 v191, 1.0, v191
	v_add_f32_e32 v192, 1.0, v192
	v_add_f32_e32 v193, 1.0, v193
	v_rcp_f32_e32 v190, v190
	v_rcp_f32_e32 v191, v191
	v_rcp_f32_e32 v192, v192
	v_rcp_f32_e32 v193, v193
	s_nop 0
	v_pk_mul_f32 v[110:111], v[110:111], v[190:191]
	v_pk_mul_f32 v[112:113], v[112:113], v[192:193]
	v_pk_mul_f32 v[110:111], v[106:107], v[110:111]
	v_pk_mul_f32 v[112:113], v[108:109], v[112:113]
	v_cvt_pk_f16_f32 v110, v110, v111
	v_cvt_pk_f16_f32 v111, v112, v113
	global_store_dwordx2 v183, v[110:111], s[96:97]
	v_pk_mul_f32 v[102:103], v[102:103], v[146:147]
	v_pk_mul_f32 v[104:105], v[104:105], v[148:149]
	v_and_b32_e32 v164, v186, v164
	v_and_b32_e32 v165, v186, v165
	v_and_b32_e32 v168, v188, v168
	v_and_b32_e32 v169, v188, v169
	v_fma_mix_f32 v102, v142, v164, v102 op_sel:[0,0,0] op_sel_hi:[0,1,0]
	v_fma_mix_f32 v103, v143, v164, v103 op_sel:[0,1,0] op_sel_hi:[0,1,0]
	v_fma_mix_f32 v104, v144, v165, v104 op_sel:[0,0,0] op_sel_hi:[0,1,0]
	v_fma_mix_f32 v105, v145, v165, v105 op_sel:[0,1,0] op_sel_hi:[0,1,0]
	v_fma_mix_f32 v102, v150, v168, v102 op_sel:[0,0,0] op_sel_hi:[0,1,0]
	v_fma_mix_f32 v103, v151, v168, v103 op_sel:[0,1,0] op_sel_hi:[0,1,0]
	v_fma_mix_f32 v104, v152, v169, v104 op_sel:[0,0,0] op_sel_hi:[0,1,0]
	v_fma_mix_f32 v105, v153, v169, v105 op_sel:[0,1,0] op_sel_hi:[0,1,0]
	v_mul_f32_e32 v190, 0xbfb8aa3b, v102
	v_mul_f32_e32 v191, 0xbfb8aa3b, v103
	v_mul_f32_e32 v192, 0xbfb8aa3b, v104
	v_mul_f32_e32 v193, 0xbfb8aa3b, v105
	v_exp_f32_e32 v190, v190
	v_exp_f32_e32 v191, v191
	v_exp_f32_e32 v192, v192
	v_exp_f32_e32 v193, v193
	v_add_f32_e32 v190, 1.0, v190
	v_add_f32_e32 v191, 1.0, v191
	v_add_f32_e32 v192, 1.0, v192
	v_add_f32_e32 v193, 1.0, v193
	v_rcp_f32_e32 v190, v190
	v_rcp_f32_e32 v191, v191
	v_rcp_f32_e32 v192, v192
	v_rcp_f32_e32 v193, v193
	s_nop 0
	v_pk_mul_f32 v[102:103], v[102:103], v[190:191]
	v_pk_mul_f32 v[104:105], v[104:105], v[192:193]
	v_pk_mul_f32 v[102:103], v[98:99], v[102:103]
	v_pk_mul_f32 v[104:105], v[100:101], v[104:105]
	v_cvt_pk_f16_f32 v102, v102, v103
	v_cvt_pk_f16_f32 v103, v104, v105
	global_store_dwordx2 v183, v[102:103], s[96:97] offset:32
	s_mov_b64 exec, s[4:5]
	v_add_u32_e32 v179, 0x3300, v201
	ds_read2_b64 v[162:165], v179 offset1:4
	ds_read2_b64 v[166:169], v179 offset0:68 offset1:72
	v_add_u32_e32 v180, 32, v200
	v_add_u32_e32 v181, s34, v180
	v_add_u32_e32 v182, -1, v180
	v_cmp_gt_u32_e32 vcc, 0xfe, v182
	v_cmp_gt_i32_e64 s[2:3], s6, v181
	v_cmp_gt_i32_e64 s[4:5], s68, v181
	v_mad_u32_u24 v183, v181, s52, v207
	s_and_b64 s[2:3], vcc, s[2:3]
	v_cndmask_b32_e64 v184, v216, v217, s[4:5]
	v_and_b32_e32 v185, v184, v181
	v_cmp_eq_u32_e32 vcc, 0, v185
	s_nop 1
	v_cndmask_b32_e64 v186, -1, 0, vcc
	v_cmp_eq_u32_e32 vcc, v185, v184
	s_nop 1
	v_cndmask_b32_e64 v188, -1, 0, vcc
	s_and_saveexec_b64 s[4:5], s[2:3]
	s_waitcnt lgkmcnt(2)
	v_pk_mul_f32 v[94:95], v[94:95], v[134:135]
	v_pk_mul_f32 v[96:97], v[96:97], v[136:137]
	v_and_b32_e32 v154, v186, v154
	v_and_b32_e32 v155, v186, v155
	v_and_b32_e32 v158, v188, v158
	v_and_b32_e32 v159, v188, v159
	v_fma_mix_f32 v94, v130, v154, v94 op_sel:[0,0,0] op_sel_hi:[0,1,0]
	v_fma_mix_f32 v95, v131, v154, v95 op_sel:[0,1,0] op_sel_hi:[0,1,0]
	v_fma_mix_f32 v96, v132, v155, v96 op_sel:[0,0,0] op_sel_hi:[0,1,0]
	v_fma_mix_f32 v97, v133, v155, v97 op_sel:[0,1,0] op_sel_hi:[0,1,0]
	v_fma_mix_f32 v94, v138, v158, v94 op_sel:[0,0,0] op_sel_hi:[0,1,0]
	v_fma_mix_f32 v95, v139, v158, v95 op_sel:[0,1,0] op_sel_hi:[0,1,0]
	v_fma_mix_f32 v96, v140, v159, v96 op_sel:[0,0,0] op_sel_hi:[0,1,0]
	v_fma_mix_f32 v97, v141, v159, v97 op_sel:[0,1,0] op_sel_hi:[0,1,0]
	v_mul_f32_e32 v190, 0xbfb8aa3b, v94
	v_mul_f32_e32 v191, 0xbfb8aa3b, v95
	v_mul_f32_e32 v192, 0xbfb8aa3b, v96
	v_mul_f32_e32 v193, 0xbfb8aa3b, v97
	v_exp_f32_e32 v190, v190
	v_exp_f32_e32 v191, v191
	v_exp_f32_e32 v192, v192
	v_exp_f32_e32 v193, v193
	v_add_f32_e32 v190, 1.0, v190
	v_add_f32_e32 v191, 1.0, v191
	v_add_f32_e32 v192, 1.0, v192
	v_add_f32_e32 v193, 1.0, v193
	v_rcp_f32_e32 v190, v190
	v_rcp_f32_e32 v191, v191
	v_rcp_f32_e32 v192, v192
	v_rcp_f32_e32 v193, v193
	s_nop 0
	v_pk_mul_f32 v[94:95], v[94:95], v[190:191]
	v_pk_mul_f32 v[96:97], v[96:97], v[192:193]
	v_pk_mul_f32 v[94:95], v[90:91], v[94:95]
	v_pk_mul_f32 v[96:97], v[92:93], v[96:97]
	v_cvt_pk_f16_f32 v94, v94, v95
	v_cvt_pk_f16_f32 v95, v96, v97
	global_store_dwordx2 v183, v[94:95], s[96:97]
	v_pk_mul_f32 v[86:87], v[86:87], v[146:147]
	v_pk_mul_f32 v[88:89], v[88:89], v[148:149]
	v_and_b32_e32 v156, v186, v156
	v_and_b32_e32 v157, v186, v157
	v_and_b32_e32 v160, v188, v160
	v_and_b32_e32 v161, v188, v161
	v_fma_mix_f32 v86, v142, v156, v86 op_sel:[0,0,0] op_sel_hi:[0,1,0]
	v_fma_mix_f32 v87, v143, v156, v87 op_sel:[0,1,0] op_sel_hi:[0,1,0]
	v_fma_mix_f32 v88, v144, v157, v88 op_sel:[0,0,0] op_sel_hi:[0,1,0]
	v_fma_mix_f32 v89, v145, v157, v89 op_sel:[0,1,0] op_sel_hi:[0,1,0]
	v_fma_mix_f32 v86, v150, v160, v86 op_sel:[0,0,0] op_sel_hi:[0,1,0]
	v_fma_mix_f32 v87, v151, v160, v87 op_sel:[0,1,0] op_sel_hi:[0,1,0]
	v_fma_mix_f32 v88, v152, v161, v88 op_sel:[0,0,0] op_sel_hi:[0,1,0]
	v_fma_mix_f32 v89, v153, v161, v89 op_sel:[0,1,0] op_sel_hi:[0,1,0]
	v_mul_f32_e32 v190, 0xbfb8aa3b, v86
	v_mul_f32_e32 v191, 0xbfb8aa3b, v87
	v_mul_f32_e32 v192, 0xbfb8aa3b, v88
	v_mul_f32_e32 v193, 0xbfb8aa3b, v89
	v_exp_f32_e32 v190, v190
	v_exp_f32_e32 v191, v191
	v_exp_f32_e32 v192, v192
	v_exp_f32_e32 v193, v193
	v_add_f32_e32 v190, 1.0, v190
	v_add_f32_e32 v191, 1.0, v191
	v_add_f32_e32 v192, 1.0, v192
	v_add_f32_e32 v193, 1.0, v193
	v_rcp_f32_e32 v190, v190
	v_rcp_f32_e32 v191, v191
	v_rcp_f32_e32 v192, v192
	v_rcp_f32_e32 v193, v193
	s_nop 0
	v_pk_mul_f32 v[86:87], v[86:87], v[190:191]
	v_pk_mul_f32 v[88:89], v[88:89], v[192:193]
	v_pk_mul_f32 v[86:87], v[82:83], v[86:87]
	v_pk_mul_f32 v[88:89], v[84:85], v[88:89]
	v_cvt_pk_f16_f32 v86, v86, v87
	v_cvt_pk_f16_f32 v87, v88, v89
	global_store_dwordx2 v183, v[86:87], s[96:97] offset:32
	s_mov_b64 exec, s[4:5]
	v_add_u32_e32 v179, 0x4400, v201
	ds_read2_b64 v[154:157], v179 offset1:4
	ds_read2_b64 v[158:161], v179 offset0:68 offset1:72
	v_add_u32_e32 v180, 48, v200
	v_add_u32_e32 v181, s34, v180
	v_add_u32_e32 v182, -1, v180
	v_cmp_gt_u32_e32 vcc, 0xfe, v182
	v_cmp_gt_i32_e64 s[2:3], s6, v181
	v_cmp_gt_i32_e64 s[4:5], s68, v181
	v_mad_u32_u24 v183, v181, s52, v207
	s_and_b64 s[2:3], vcc, s[2:3]
	v_cndmask_b32_e64 v184, v216, v217, s[4:5]
	v_and_b32_e32 v185, v184, v181
	v_cmp_eq_u32_e32 vcc, 0, v185
	s_nop 1
	v_cndmask_b32_e64 v186, -1, 0, vcc
	v_cmp_eq_u32_e32 vcc, v185, v184
	s_nop 1
	v_cndmask_b32_e64 v188, -1, 0, vcc
	s_and_saveexec_b64 s[4:5], s[2:3]
	s_waitcnt lgkmcnt(2)
	v_pk_mul_f32 v[78:79], v[78:79], v[134:135]
	v_pk_mul_f32 v[80:81], v[80:81], v[136:137]
	v_and_b32_e32 v162, v186, v162
	v_and_b32_e32 v163, v186, v163
	v_and_b32_e32 v166, v188, v166
	v_and_b32_e32 v167, v188, v167
	v_fma_mix_f32 v78, v130, v162, v78 op_sel:[0,0,0] op_sel_hi:[0,1,0]
	v_fma_mix_f32 v79, v131, v162, v79 op_sel:[0,1,0] op_sel_hi:[0,1,0]
	v_fma_mix_f32 v80, v132, v163, v80 op_sel:[0,0,0] op_sel_hi:[0,1,0]
	v_fma_mix_f32 v81, v133, v163, v81 op_sel:[0,1,0] op_sel_hi:[0,1,0]
	v_fma_mix_f32 v78, v138, v166, v78 op_sel:[0,0,0] op_sel_hi:[0,1,0]
	v_fma_mix_f32 v79, v139, v166, v79 op_sel:[0,1,0] op_sel_hi:[0,1,0]
	v_fma_mix_f32 v80, v140, v167, v80 op_sel:[0,0,0] op_sel_hi:[0,1,0]
	v_fma_mix_f32 v81, v141, v167, v81 op_sel:[0,1,0] op_sel_hi:[0,1,0]
	v_mul_f32_e32 v190, 0xbfb8aa3b, v78
	v_mul_f32_e32 v191, 0xbfb8aa3b, v79
	v_mul_f32_e32 v192, 0xbfb8aa3b, v80
	v_mul_f32_e32 v193, 0xbfb8aa3b, v81
	v_exp_f32_e32 v190, v190
	v_exp_f32_e32 v191, v191
	v_exp_f32_e32 v192, v192
	v_exp_f32_e32 v193, v193
	v_add_f32_e32 v190, 1.0, v190
	v_add_f32_e32 v191, 1.0, v191
	v_add_f32_e32 v192, 1.0, v192
	v_add_f32_e32 v193, 1.0, v193
	v_rcp_f32_e32 v190, v190
	v_rcp_f32_e32 v191, v191
	v_rcp_f32_e32 v192, v192
	v_rcp_f32_e32 v193, v193
	s_nop 0
	v_pk_mul_f32 v[78:79], v[78:79], v[190:191]
	v_pk_mul_f32 v[80:81], v[80:81], v[192:193]
	v_pk_mul_f32 v[78:79], v[74:75], v[78:79]
	v_pk_mul_f32 v[80:81], v[76:77], v[80:81]
	v_cvt_pk_f16_f32 v78, v78, v79
	v_cvt_pk_f16_f32 v79, v80, v81
	global_store_dwordx2 v183, v[78:79], s[96:97]
	v_pk_mul_f32 v[70:71], v[70:71], v[146:147]
	v_pk_mul_f32 v[72:73], v[72:73], v[148:149]
	v_and_b32_e32 v164, v186, v164
	v_and_b32_e32 v165, v186, v165
	v_and_b32_e32 v168, v188, v168
	v_and_b32_e32 v169, v188, v169
	v_fma_mix_f32 v70, v142, v164, v70 op_sel:[0,0,0] op_sel_hi:[0,1,0]
	v_fma_mix_f32 v71, v143, v164, v71 op_sel:[0,1,0] op_sel_hi:[0,1,0]
	v_fma_mix_f32 v72, v144, v165, v72 op_sel:[0,0,0] op_sel_hi:[0,1,0]
	v_fma_mix_f32 v73, v145, v165, v73 op_sel:[0,1,0] op_sel_hi:[0,1,0]
	v_fma_mix_f32 v70, v150, v168, v70 op_sel:[0,0,0] op_sel_hi:[0,1,0]
	v_fma_mix_f32 v71, v151, v168, v71 op_sel:[0,1,0] op_sel_hi:[0,1,0]
	v_fma_mix_f32 v72, v152, v169, v72 op_sel:[0,0,0] op_sel_hi:[0,1,0]
	v_fma_mix_f32 v73, v153, v169, v73 op_sel:[0,1,0] op_sel_hi:[0,1,0]
	v_mul_f32_e32 v190, 0xbfb8aa3b, v70
	v_mul_f32_e32 v191, 0xbfb8aa3b, v71
	v_mul_f32_e32 v192, 0xbfb8aa3b, v72
	v_mul_f32_e32 v193, 0xbfb8aa3b, v73
	v_exp_f32_e32 v190, v190
	v_exp_f32_e32 v191, v191
	v_exp_f32_e32 v192, v192
	v_exp_f32_e32 v193, v193
	v_add_f32_e32 v190, 1.0, v190
	v_add_f32_e32 v191, 1.0, v191
	v_add_f32_e32 v192, 1.0, v192
	v_add_f32_e32 v193, 1.0, v193
	v_rcp_f32_e32 v190, v190
	v_rcp_f32_e32 v191, v191
	v_rcp_f32_e32 v192, v192
	v_rcp_f32_e32 v193, v193
	s_nop 0
	v_pk_mul_f32 v[70:71], v[70:71], v[190:191]
	v_pk_mul_f32 v[72:73], v[72:73], v[192:193]
	v_pk_mul_f32 v[70:71], v[66:67], v[70:71]
	v_pk_mul_f32 v[72:73], v[68:69], v[72:73]
	v_cvt_pk_f16_f32 v70, v70, v71
	v_cvt_pk_f16_f32 v71, v72, v73
	global_store_dwordx2 v183, v[70:71], s[96:97] offset:32
	s_mov_b64 exec, s[4:5]
	v_add_u32_e32 v179, 0x5500, v201
	ds_read2_b64 v[162:165], v179 offset1:4
	ds_read2_b64 v[166:169], v179 offset0:68 offset1:72
	v_add_u32_e32 v180, 64, v200
	v_add_u32_e32 v181, s34, v180
	v_add_u32_e32 v182, -1, v180
	v_cmp_gt_u32_e32 vcc, 0xfe, v182
	v_cmp_gt_i32_e64 s[2:3], s6, v181
	v_cmp_gt_i32_e64 s[4:5], s68, v181
	v_mad_u32_u24 v183, v181, s52, v207
	s_and_b64 s[2:3], vcc, s[2:3]
	v_cndmask_b32_e64 v184, v216, v217, s[4:5]
	v_and_b32_e32 v185, v184, v181
	v_cmp_eq_u32_e32 vcc, 0, v185
	s_nop 1
	v_cndmask_b32_e64 v186, -1, 0, vcc
	v_cmp_eq_u32_e32 vcc, v185, v184
	s_nop 1
	v_cndmask_b32_e64 v188, -1, 0, vcc
	s_and_saveexec_b64 s[4:5], s[2:3]
	s_waitcnt lgkmcnt(2)
	v_pk_mul_f32 v[62:63], v[62:63], v[134:135]
	v_pk_mul_f32 v[64:65], v[64:65], v[136:137]
	v_and_b32_e32 v154, v186, v154
	v_and_b32_e32 v155, v186, v155
	v_and_b32_e32 v158, v188, v158
	v_and_b32_e32 v159, v188, v159
	v_fma_mix_f32 v62, v130, v154, v62 op_sel:[0,0,0] op_sel_hi:[0,1,0]
	v_fma_mix_f32 v63, v131, v154, v63 op_sel:[0,1,0] op_sel_hi:[0,1,0]
	v_fma_mix_f32 v64, v132, v155, v64 op_sel:[0,0,0] op_sel_hi:[0,1,0]
	v_fma_mix_f32 v65, v133, v155, v65 op_sel:[0,1,0] op_sel_hi:[0,1,0]
	v_fma_mix_f32 v62, v138, v158, v62 op_sel:[0,0,0] op_sel_hi:[0,1,0]
	v_fma_mix_f32 v63, v139, v158, v63 op_sel:[0,1,0] op_sel_hi:[0,1,0]
	v_fma_mix_f32 v64, v140, v159, v64 op_sel:[0,0,0] op_sel_hi:[0,1,0]
	v_fma_mix_f32 v65, v141, v159, v65 op_sel:[0,1,0] op_sel_hi:[0,1,0]
	v_mul_f32_e32 v190, 0xbfb8aa3b, v62
	v_mul_f32_e32 v191, 0xbfb8aa3b, v63
	v_mul_f32_e32 v192, 0xbfb8aa3b, v64
	v_mul_f32_e32 v193, 0xbfb8aa3b, v65
	v_exp_f32_e32 v190, v190
	v_exp_f32_e32 v191, v191
	v_exp_f32_e32 v192, v192
	v_exp_f32_e32 v193, v193
	v_add_f32_e32 v190, 1.0, v190
	v_add_f32_e32 v191, 1.0, v191
	v_add_f32_e32 v192, 1.0, v192
	v_add_f32_e32 v193, 1.0, v193
	v_rcp_f32_e32 v190, v190
	v_rcp_f32_e32 v191, v191
	v_rcp_f32_e32 v192, v192
	v_rcp_f32_e32 v193, v193
	s_nop 0
	v_pk_mul_f32 v[62:63], v[62:63], v[190:191]
	v_pk_mul_f32 v[64:65], v[64:65], v[192:193]
	v_pk_mul_f32 v[62:63], v[58:59], v[62:63]
	v_pk_mul_f32 v[64:65], v[60:61], v[64:65]
	v_cvt_pk_f16_f32 v62, v62, v63
	v_cvt_pk_f16_f32 v63, v64, v65
	global_store_dwordx2 v183, v[62:63], s[96:97]
	v_pk_mul_f32 v[54:55], v[54:55], v[146:147]
	v_pk_mul_f32 v[56:57], v[56:57], v[148:149]
	v_and_b32_e32 v156, v186, v156
	v_and_b32_e32 v157, v186, v157
	v_and_b32_e32 v160, v188, v160
	v_and_b32_e32 v161, v188, v161
	v_fma_mix_f32 v54, v142, v156, v54 op_sel:[0,0,0] op_sel_hi:[0,1,0]
	v_fma_mix_f32 v55, v143, v156, v55 op_sel:[0,1,0] op_sel_hi:[0,1,0]
	v_fma_mix_f32 v56, v144, v157, v56 op_sel:[0,0,0] op_sel_hi:[0,1,0]
	v_fma_mix_f32 v57, v145, v157, v57 op_sel:[0,1,0] op_sel_hi:[0,1,0]
	v_fma_mix_f32 v54, v150, v160, v54 op_sel:[0,0,0] op_sel_hi:[0,1,0]
	v_fma_mix_f32 v55, v151, v160, v55 op_sel:[0,1,0] op_sel_hi:[0,1,0]
	v_fma_mix_f32 v56, v152, v161, v56 op_sel:[0,0,0] op_sel_hi:[0,1,0]
	v_fma_mix_f32 v57, v153, v161, v57 op_sel:[0,1,0] op_sel_hi:[0,1,0]
	v_mul_f32_e32 v190, 0xbfb8aa3b, v54
	v_mul_f32_e32 v191, 0xbfb8aa3b, v55
	v_mul_f32_e32 v192, 0xbfb8aa3b, v56
	v_mul_f32_e32 v193, 0xbfb8aa3b, v57
	v_exp_f32_e32 v190, v190
	v_exp_f32_e32 v191, v191
	v_exp_f32_e32 v192, v192
	v_exp_f32_e32 v193, v193
	v_add_f32_e32 v190, 1.0, v190
	v_add_f32_e32 v191, 1.0, v191
	v_add_f32_e32 v192, 1.0, v192
	v_add_f32_e32 v193, 1.0, v193
	v_rcp_f32_e32 v190, v190
	v_rcp_f32_e32 v191, v191
	v_rcp_f32_e32 v192, v192
	v_rcp_f32_e32 v193, v193
	s_nop 0
	v_pk_mul_f32 v[54:55], v[54:55], v[190:191]
	v_pk_mul_f32 v[56:57], v[56:57], v[192:193]
	v_pk_mul_f32 v[54:55], v[50:51], v[54:55]
	v_pk_mul_f32 v[56:57], v[52:53], v[56:57]
	v_cvt_pk_f16_f32 v54, v54, v55
	v_cvt_pk_f16_f32 v55, v56, v57
	global_store_dwordx2 v183, v[54:55], s[96:97] offset:32
	s_mov_b64 exec, s[4:5]
	v_add_u32_e32 v179, 0x6600, v201
	ds_read2_b64 v[154:157], v179 offset1:4
	ds_read2_b64 v[158:161], v179 offset0:68 offset1:72
	v_add_u32_e32 v180, 80, v200
	v_add_u32_e32 v181, s34, v180
	v_add_u32_e32 v182, -1, v180
	v_cmp_gt_u32_e32 vcc, 0xfe, v182
	v_cmp_gt_i32_e64 s[2:3], s6, v181
	v_cmp_gt_i32_e64 s[4:5], s68, v181
	v_mad_u32_u24 v183, v181, s52, v207
	s_and_b64 s[2:3], vcc, s[2:3]
	v_cndmask_b32_e64 v184, v216, v217, s[4:5]
	v_and_b32_e32 v185, v184, v181
	v_cmp_eq_u32_e32 vcc, 0, v185
	s_nop 1
	v_cndmask_b32_e64 v186, -1, 0, vcc
	v_cmp_eq_u32_e32 vcc, v185, v184
	s_nop 1
	v_cndmask_b32_e64 v188, -1, 0, vcc
	s_and_saveexec_b64 s[4:5], s[2:3]
	s_waitcnt lgkmcnt(2)
	v_pk_mul_f32 v[46:47], v[46:47], v[134:135]
	v_pk_mul_f32 v[48:49], v[48:49], v[136:137]
	v_and_b32_e32 v162, v186, v162
	v_and_b32_e32 v163, v186, v163
	v_and_b32_e32 v166, v188, v166
	v_and_b32_e32 v167, v188, v167
	v_fma_mix_f32 v46, v130, v162, v46 op_sel:[0,0,0] op_sel_hi:[0,1,0]
	v_fma_mix_f32 v47, v131, v162, v47 op_sel:[0,1,0] op_sel_hi:[0,1,0]
	v_fma_mix_f32 v48, v132, v163, v48 op_sel:[0,0,0] op_sel_hi:[0,1,0]
	v_fma_mix_f32 v49, v133, v163, v49 op_sel:[0,1,0] op_sel_hi:[0,1,0]
	v_fma_mix_f32 v46, v138, v166, v46 op_sel:[0,0,0] op_sel_hi:[0,1,0]
	v_fma_mix_f32 v47, v139, v166, v47 op_sel:[0,1,0] op_sel_hi:[0,1,0]
	v_fma_mix_f32 v48, v140, v167, v48 op_sel:[0,0,0] op_sel_hi:[0,1,0]
	v_fma_mix_f32 v49, v141, v167, v49 op_sel:[0,1,0] op_sel_hi:[0,1,0]
	v_mul_f32_e32 v190, 0xbfb8aa3b, v46
	v_mul_f32_e32 v191, 0xbfb8aa3b, v47
	v_mul_f32_e32 v192, 0xbfb8aa3b, v48
	v_mul_f32_e32 v193, 0xbfb8aa3b, v49
	v_exp_f32_e32 v190, v190
	v_exp_f32_e32 v191, v191
	v_exp_f32_e32 v192, v192
	v_exp_f32_e32 v193, v193
	v_add_f32_e32 v190, 1.0, v190
	v_add_f32_e32 v191, 1.0, v191
	v_add_f32_e32 v192, 1.0, v192
	v_add_f32_e32 v193, 1.0, v193
	v_rcp_f32_e32 v190, v190
	v_rcp_f32_e32 v191, v191
	v_rcp_f32_e32 v192, v192
	v_rcp_f32_e32 v193, v193
	s_nop 0
	v_pk_mul_f32 v[46:47], v[46:47], v[190:191]
	v_pk_mul_f32 v[48:49], v[48:49], v[192:193]
	v_pk_mul_f32 v[46:47], v[42:43], v[46:47]
	v_pk_mul_f32 v[48:49], v[44:45], v[48:49]
	v_cvt_pk_f16_f32 v46, v46, v47
	v_cvt_pk_f16_f32 v47, v48, v49
	global_store_dwordx2 v183, v[46:47], s[96:97]
	v_pk_mul_f32 v[38:39], v[38:39], v[146:147]
	v_pk_mul_f32 v[40:41], v[40:41], v[148:149]
	v_and_b32_e32 v164, v186, v164
	v_and_b32_e32 v165, v186, v165
	v_and_b32_e32 v168, v188, v168
	v_and_b32_e32 v169, v188, v169
	v_fma_mix_f32 v38, v142, v164, v38 op_sel:[0,0,0] op_sel_hi:[0,1,0]
	v_fma_mix_f32 v39, v143, v164, v39 op_sel:[0,1,0] op_sel_hi:[0,1,0]
	v_fma_mix_f32 v40, v144, v165, v40 op_sel:[0,0,0] op_sel_hi:[0,1,0]
	v_fma_mix_f32 v41, v145, v165, v41 op_sel:[0,1,0] op_sel_hi:[0,1,0]
	v_fma_mix_f32 v38, v150, v168, v38 op_sel:[0,0,0] op_sel_hi:[0,1,0]
	v_fma_mix_f32 v39, v151, v168, v39 op_sel:[0,1,0] op_sel_hi:[0,1,0]
	v_fma_mix_f32 v40, v152, v169, v40 op_sel:[0,0,0] op_sel_hi:[0,1,0]
	v_fma_mix_f32 v41, v153, v169, v41 op_sel:[0,1,0] op_sel_hi:[0,1,0]
	v_mul_f32_e32 v190, 0xbfb8aa3b, v38
	v_mul_f32_e32 v191, 0xbfb8aa3b, v39
	v_mul_f32_e32 v192, 0xbfb8aa3b, v40
	v_mul_f32_e32 v193, 0xbfb8aa3b, v41
	v_exp_f32_e32 v190, v190
	v_exp_f32_e32 v191, v191
	v_exp_f32_e32 v192, v192
	v_exp_f32_e32 v193, v193
	v_add_f32_e32 v190, 1.0, v190
	v_add_f32_e32 v191, 1.0, v191
	v_add_f32_e32 v192, 1.0, v192
	v_add_f32_e32 v193, 1.0, v193
	v_rcp_f32_e32 v190, v190
	v_rcp_f32_e32 v191, v191
	v_rcp_f32_e32 v192, v192
	v_rcp_f32_e32 v193, v193
	s_nop 0
	v_pk_mul_f32 v[38:39], v[38:39], v[190:191]
	v_pk_mul_f32 v[40:41], v[40:41], v[192:193]
	v_pk_mul_f32 v[38:39], v[34:35], v[38:39]
	v_pk_mul_f32 v[40:41], v[36:37], v[40:41]
	v_cvt_pk_f16_f32 v38, v38, v39
	v_cvt_pk_f16_f32 v39, v40, v41
	global_store_dwordx2 v183, v[38:39], s[96:97] offset:32
	s_mov_b64 exec, s[4:5]
	v_add_u32_e32 v179, 0x7700, v201
	ds_read2_b64 v[162:165], v179 offset1:4
	ds_read2_b64 v[166:169], v179 offset0:68 offset1:72
	v_add_u32_e32 v180, 96, v200
	v_add_u32_e32 v181, s34, v180
	v_add_u32_e32 v182, -1, v180
	v_cmp_gt_u32_e32 vcc, 0xfe, v182
	v_cmp_gt_i32_e64 s[2:3], s6, v181
	v_cmp_gt_i32_e64 s[4:5], s68, v181
	v_mad_u32_u24 v183, v181, s52, v207
	s_and_b64 s[2:3], vcc, s[2:3]
	v_cndmask_b32_e64 v184, v216, v217, s[4:5]
	v_and_b32_e32 v185, v184, v181
	v_cmp_eq_u32_e32 vcc, 0, v185
	s_nop 1
	v_cndmask_b32_e64 v186, -1, 0, vcc
	v_cmp_eq_u32_e32 vcc, v185, v184
	s_nop 1
	v_cndmask_b32_e64 v188, -1, 0, vcc
	s_and_saveexec_b64 s[4:5], s[2:3]
	s_waitcnt lgkmcnt(2)
	v_pk_mul_f32 v[30:31], v[30:31], v[134:135]
	v_pk_mul_f32 v[32:33], v[32:33], v[136:137]
	v_and_b32_e32 v154, v186, v154
	v_and_b32_e32 v155, v186, v155
	v_and_b32_e32 v158, v188, v158
	v_and_b32_e32 v159, v188, v159
	v_fma_mix_f32 v30, v130, v154, v30 op_sel:[0,0,0] op_sel_hi:[0,1,0]
	v_fma_mix_f32 v31, v131, v154, v31 op_sel:[0,1,0] op_sel_hi:[0,1,0]
	v_fma_mix_f32 v32, v132, v155, v32 op_sel:[0,0,0] op_sel_hi:[0,1,0]
	v_fma_mix_f32 v33, v133, v155, v33 op_sel:[0,1,0] op_sel_hi:[0,1,0]
	v_fma_mix_f32 v30, v138, v158, v30 op_sel:[0,0,0] op_sel_hi:[0,1,0]
	v_fma_mix_f32 v31, v139, v158, v31 op_sel:[0,1,0] op_sel_hi:[0,1,0]
	v_fma_mix_f32 v32, v140, v159, v32 op_sel:[0,0,0] op_sel_hi:[0,1,0]
	v_fma_mix_f32 v33, v141, v159, v33 op_sel:[0,1,0] op_sel_hi:[0,1,0]
	v_mul_f32_e32 v190, 0xbfb8aa3b, v30
	v_mul_f32_e32 v191, 0xbfb8aa3b, v31
	v_mul_f32_e32 v192, 0xbfb8aa3b, v32
	v_mul_f32_e32 v193, 0xbfb8aa3b, v33
	v_exp_f32_e32 v190, v190
	v_exp_f32_e32 v191, v191
	v_exp_f32_e32 v192, v192
	v_exp_f32_e32 v193, v193
	v_add_f32_e32 v190, 1.0, v190
	v_add_f32_e32 v191, 1.0, v191
	v_add_f32_e32 v192, 1.0, v192
	v_add_f32_e32 v193, 1.0, v193
	v_rcp_f32_e32 v190, v190
	v_rcp_f32_e32 v191, v191
	v_rcp_f32_e32 v192, v192
	v_rcp_f32_e32 v193, v193
	s_nop 0
	v_pk_mul_f32 v[30:31], v[30:31], v[190:191]
	v_pk_mul_f32 v[32:33], v[32:33], v[192:193]
	v_pk_mul_f32 v[30:31], v[26:27], v[30:31]
	v_pk_mul_f32 v[32:33], v[28:29], v[32:33]
	v_cvt_pk_f16_f32 v30, v30, v31
	v_cvt_pk_f16_f32 v31, v32, v33
	global_store_dwordx2 v183, v[30:31], s[96:97]
	v_pk_mul_f32 v[22:23], v[22:23], v[146:147]
	v_pk_mul_f32 v[24:25], v[24:25], v[148:149]
	v_and_b32_e32 v156, v186, v156
	v_and_b32_e32 v157, v186, v157
	v_and_b32_e32 v160, v188, v160
	v_and_b32_e32 v161, v188, v161
	v_fma_mix_f32 v22, v142, v156, v22 op_sel:[0,0,0] op_sel_hi:[0,1,0]
	v_fma_mix_f32 v23, v143, v156, v23 op_sel:[0,1,0] op_sel_hi:[0,1,0]
	v_fma_mix_f32 v24, v144, v157, v24 op_sel:[0,0,0] op_sel_hi:[0,1,0]
	v_fma_mix_f32 v25, v145, v157, v25 op_sel:[0,1,0] op_sel_hi:[0,1,0]
	v_fma_mix_f32 v22, v150, v160, v22 op_sel:[0,0,0] op_sel_hi:[0,1,0]
	v_fma_mix_f32 v23, v151, v160, v23 op_sel:[0,1,0] op_sel_hi:[0,1,0]
	v_fma_mix_f32 v24, v152, v161, v24 op_sel:[0,0,0] op_sel_hi:[0,1,0]
	v_fma_mix_f32 v25, v153, v161, v25 op_sel:[0,1,0] op_sel_hi:[0,1,0]
	v_mul_f32_e32 v190, 0xbfb8aa3b, v22
	v_mul_f32_e32 v191, 0xbfb8aa3b, v23
	v_mul_f32_e32 v192, 0xbfb8aa3b, v24
	v_mul_f32_e32 v193, 0xbfb8aa3b, v25
	v_exp_f32_e32 v190, v190
	v_exp_f32_e32 v191, v191
	v_exp_f32_e32 v192, v192
	v_exp_f32_e32 v193, v193
	v_add_f32_e32 v190, 1.0, v190
	v_add_f32_e32 v191, 1.0, v191
	v_add_f32_e32 v192, 1.0, v192
	v_add_f32_e32 v193, 1.0, v193
	v_rcp_f32_e32 v190, v190
	v_rcp_f32_e32 v191, v191
	v_rcp_f32_e32 v192, v192
	v_rcp_f32_e32 v193, v193
	s_nop 0
	v_pk_mul_f32 v[22:23], v[22:23], v[190:191]
	v_pk_mul_f32 v[24:25], v[24:25], v[192:193]
	v_pk_mul_f32 v[22:23], v[18:19], v[22:23]
	v_pk_mul_f32 v[24:25], v[20:21], v[24:25]
	v_cvt_pk_f16_f32 v22, v22, v23
	v_cvt_pk_f16_f32 v23, v24, v25
	global_store_dwordx2 v183, v[22:23], s[96:97] offset:32
	s_mov_b64 exec, s[4:5]
	v_add_u32_e32 v180, 112, v200
	v_add_u32_e32 v181, s34, v180
	v_add_u32_e32 v182, -1, v180
	v_cmp_gt_u32_e32 vcc, 0xfe, v182
	v_cmp_gt_i32_e64 s[2:3], s6, v181
	v_cmp_gt_i32_e64 s[4:5], s68, v181
	v_mad_u32_u24 v183, v181, s52, v207
	s_and_b64 s[2:3], vcc, s[2:3]
	v_cndmask_b32_e64 v184, v216, v217, s[4:5]
	v_and_b32_e32 v185, v184, v181
	v_cmp_eq_u32_e32 vcc, 0, v185
	s_nop 1
	v_cndmask_b32_e64 v186, -1, 0, vcc
	v_cmp_eq_u32_e32 vcc, v185, v184
	s_nop 1
	v_cndmask_b32_e64 v188, -1, 0, vcc
	s_and_saveexec_b64 s[4:5], s[2:3]
	s_waitcnt lgkmcnt(0)
	v_pk_mul_f32 v[14:15], v[14:15], v[134:135]
	v_pk_mul_f32 v[16:17], v[16:17], v[136:137]
	v_and_b32_e32 v162, v186, v162
	v_and_b32_e32 v163, v186, v163
	v_and_b32_e32 v166, v188, v166
	v_and_b32_e32 v167, v188, v167
	v_fma_mix_f32 v14, v130, v162, v14 op_sel:[0,0,0] op_sel_hi:[0,1,0]
	v_fma_mix_f32 v15, v131, v162, v15 op_sel:[0,1,0] op_sel_hi:[0,1,0]
	v_fma_mix_f32 v16, v132, v163, v16 op_sel:[0,0,0] op_sel_hi:[0,1,0]
	v_fma_mix_f32 v17, v133, v163, v17 op_sel:[0,1,0] op_sel_hi:[0,1,0]
	v_fma_mix_f32 v14, v138, v166, v14 op_sel:[0,0,0] op_sel_hi:[0,1,0]
	v_fma_mix_f32 v15, v139, v166, v15 op_sel:[0,1,0] op_sel_hi:[0,1,0]
	v_fma_mix_f32 v16, v140, v167, v16 op_sel:[0,0,0] op_sel_hi:[0,1,0]
	v_fma_mix_f32 v17, v141, v167, v17 op_sel:[0,1,0] op_sel_hi:[0,1,0]
	v_mul_f32_e32 v190, 0xbfb8aa3b, v14
	v_mul_f32_e32 v191, 0xbfb8aa3b, v15
	v_mul_f32_e32 v192, 0xbfb8aa3b, v16
	v_mul_f32_e32 v193, 0xbfb8aa3b, v17
	v_exp_f32_e32 v190, v190
	v_exp_f32_e32 v191, v191
	v_exp_f32_e32 v192, v192
	v_exp_f32_e32 v193, v193
	v_add_f32_e32 v190, 1.0, v190
	v_add_f32_e32 v191, 1.0, v191
	v_add_f32_e32 v192, 1.0, v192
	v_add_f32_e32 v193, 1.0, v193
	v_rcp_f32_e32 v190, v190
	v_rcp_f32_e32 v191, v191
	v_rcp_f32_e32 v192, v192
	v_rcp_f32_e32 v193, v193
	s_nop 0
	v_pk_mul_f32 v[14:15], v[14:15], v[190:191]
	v_pk_mul_f32 v[16:17], v[16:17], v[192:193]
	v_pk_mul_f32 v[14:15], v[10:11], v[14:15]
	v_pk_mul_f32 v[16:17], v[12:13], v[16:17]
	v_cvt_pk_f16_f32 v14, v14, v15
	v_cvt_pk_f16_f32 v15, v16, v17
	global_store_dwordx2 v183, v[14:15], s[96:97]
	v_pk_mul_f32 v[6:7], v[6:7], v[146:147]
	v_pk_mul_f32 v[8:9], v[8:9], v[148:149]
	v_and_b32_e32 v164, v186, v164
	v_and_b32_e32 v165, v186, v165
	v_and_b32_e32 v168, v188, v168
	v_and_b32_e32 v169, v188, v169
	v_fma_mix_f32 v6, v142, v164, v6 op_sel:[0,0,0] op_sel_hi:[0,1,0]
	v_fma_mix_f32 v7, v143, v164, v7 op_sel:[0,1,0] op_sel_hi:[0,1,0]
	v_fma_mix_f32 v8, v144, v165, v8 op_sel:[0,0,0] op_sel_hi:[0,1,0]
	v_fma_mix_f32 v9, v145, v165, v9 op_sel:[0,1,0] op_sel_hi:[0,1,0]
	v_fma_mix_f32 v6, v150, v168, v6 op_sel:[0,0,0] op_sel_hi:[0,1,0]
	v_fma_mix_f32 v7, v151, v168, v7 op_sel:[0,1,0] op_sel_hi:[0,1,0]
	v_fma_mix_f32 v8, v152, v169, v8 op_sel:[0,0,0] op_sel_hi:[0,1,0]
	v_fma_mix_f32 v9, v153, v169, v9 op_sel:[0,1,0] op_sel_hi:[0,1,0]
	v_mul_f32_e32 v190, 0xbfb8aa3b, v6
	v_mul_f32_e32 v191, 0xbfb8aa3b, v7
	v_mul_f32_e32 v192, 0xbfb8aa3b, v8
	v_mul_f32_e32 v193, 0xbfb8aa3b, v9
	v_exp_f32_e32 v190, v190
	v_exp_f32_e32 v191, v191
	v_exp_f32_e32 v192, v192
	v_exp_f32_e32 v193, v193
	v_add_f32_e32 v190, 1.0, v190
	v_add_f32_e32 v191, 1.0, v191
	v_add_f32_e32 v192, 1.0, v192
	v_add_f32_e32 v193, 1.0, v193
	v_rcp_f32_e32 v190, v190
	v_rcp_f32_e32 v191, v191
	v_rcp_f32_e32 v192, v192
	v_rcp_f32_e32 v193, v193
	s_nop 0
	v_pk_mul_f32 v[6:7], v[6:7], v[190:191]
	v_pk_mul_f32 v[8:9], v[8:9], v[192:193]
	v_pk_mul_f32 v[6:7], v[2:3], v[6:7]
	v_pk_mul_f32 v[8:9], v[4:5], v[8:9]
	v_cvt_pk_f16_f32 v6, v6, v7
	v_cvt_pk_f16_f32 v7, v8, v9
	global_store_dwordx2 v183, v[6:7], s[96:97] offset:32
	s_mov_b64 exec, s[4:5]
	s_cmp_lg_u32 s35, 0
	s_cbranch_scc1 .Lp4_cont
	s_branch .LBB0_1135
